# attn M phase: PV V-transpose reads reordered, counted lgkmcnt waits per PV MFMA instead of lgkmcnt(0)
# speedup vs baseline: 1.0282x; 1.0282x over previous
; #define LAS __attribute__((address_space(3)))
; __device__ __forceinline__ void qkt(f32x16& p0, f32x16& p1, const LAS unsigned char* Ks, const bf16x8* qr, const f32x16& negm, int r32, int hi) {
;   bf16x8 kf[12];
; #pragma unroll
;   for (int d0 = 0; d0 < 6; ++d0) { const int cb = (d0 * 16 + hi * 8) * 2;
;     kf[2 * d0] = *(const LAS bf16x8*)(Ks + KSWZ(r32, cb)); kf[2 * d0 + 1] = *(const LAS bf16x8*)(Ks + KSWZ(32 + r32, cb)); }
;   SBAR();
;   p0 = __builtin_amdgcn_mfma_f32_32x32x16_bf16(kf[0], qr[0], negm, 0, 0, 0); p1 = __builtin_amdgcn_mfma_f32_32x32x16_bf16(kf[1], qr[0], negm, 0, 0, 0);
; #pragma unroll
;   for (int d0 = 1; d0 < 6; ++d0) { p0 = __builtin_amdgcn_mfma_f32_32x32x16_bf16(kf[2 * d0], qr[d0], p0, 0, 0, 0); p1 = __builtin_amdgcn_mfma_f32_32x32x16_bf16(kf[2 * d0 + 1], qr[d0], p1, 0, 0, 0); }
; }
; __device__ __forceinline__ int v_st(int k, int c) { const int kk = (k & ~0xC) | ((k & 4) << 1) | ((k & 8) >> 1); return ((kk >> 3) * 4 + (c >> 5)) * 512 + ((kk & 7) * 32 + (c & 31)) * 2; }
; __device__ __forceinline__ int v_rd_base(int lane) { return ((lane & 3) << 3) | (((lane >> 2) & 3) << 6) | (((lane >> 4) & 1) << 5) | (((lane >> 5) & 1) << 8); }
; template <int OFF> __device__ __forceinline__ s16x4 tr_read(int vb) {
;   s16x4 r; asm volatile("ds_read_b64_tr_b16 %0, %1 offset:%2" : "=&v"(r) : "v"(vb), "i"(OFF) : "memory"); return r;
; }
; __device__ __forceinline__ void pv_d0(f32x16* o, int vb, bf16x8 pa0, bf16x8 pa1, bf16x8 pa2, bf16x8 pa3) {
;   const s16x4 a0 = tr_read<v_rd_off(0, 0, 0)>(vb), b0 = tr_read<v_rd_off(0, 0, 1)>(vb), a1 = tr_read<v_rd_off(0, 1, 0)>(vb), b1 = tr_read<v_rd_off(0, 1, 1)>(vb);
;   const s16x4 a2 = tr_read<v_rd_off(0, 2, 0)>(vb), b2 = tr_read<v_rd_off(0, 2, 1)>(vb), a3 = tr_read<v_rd_off(0, 3, 0)>(vb), b3 = tr_read<v_rd_off(0, 3, 1)>(vb);
;   const s16x4 c0 = tr_read<v_rd_off(1, 0, 0)>(vb), d0 = tr_read<v_rd_off(1, 0, 1)>(vb), c1 = tr_read<v_rd_off(1, 1, 0)>(vb), d1 = tr_read<v_rd_off(1, 1, 1)>(vb);
;   const s16x4 c2 = tr_read<v_rd_off(1, 2, 0)>(vb), d2 = tr_read<v_rd_off(1, 2, 1)>(vb), c3 = tr_read<v_rd_off(1, 3, 0)>(vb), d3 = tr_read<v_rd_off(1, 3, 1)>(vb);
;   asm volatile("s_waitcnt lgkmcnt(0)" ::: "memory"); SBAR();
;     ...
;   o[0] = __builtin_amdgcn_mfma_f32_32x32x16_bf16(pa0, PK(a0, b0), o[0], 0, 0, 0); o[1] = __builtin_amdgcn_mfma_f32_32x32x16_bf16(pa0, PK(c0, d0), o[1], 0, 0, 0);
.LBB0_524:
	s_mov_b32 s22, s0
	s_setprio 2
	v_add_u32_e32 v174, s22, v156
	ds_read_b64_tr_b16 v[66:67], v174 offset:0
	ds_read_b64_tr_b16 v[68:69], v174 offset:0x800
	ds_read_b64_tr_b16 v[158:159], v174 offset:0x200
	ds_read_b64_tr_b16 v[160:161], v174 offset:0xa00
	ds_read_b64_tr_b16 v[70:71], v174 offset:0x1000
	ds_read_b64_tr_b16 v[72:73], v174 offset:0x1800
	ds_read_b64_tr_b16 v[162:163], v174 offset:0x1200
	ds_read_b64_tr_b16 v[164:165], v174 offset:0x1a00
	ds_read_b64_tr_b16 v[74:75], v174 offset:0x2000
	ds_read_b64_tr_b16 v[76:77], v174 offset:0x2800
	ds_read_b64_tr_b16 v[166:167], v174 offset:0x2200
	ds_read_b64_tr_b16 v[168:169], v174 offset:0x2a00
	ds_read_b64_tr_b16 v[78:79], v174 offset:0x3000
	ds_read_b64_tr_b16 v[80:81], v174 offset:0x3800
	ds_read_b64_tr_b16 v[170:171], v174 offset:0x3200
	ds_read_b64_tr_b16 v[172:173], v174 offset:0x3a00
	s_waitcnt lgkmcnt(14)
	v_mfma_f32_32x32x16_bf16 v[34:49], v[62:65], v[66:69], v[34:49]
	s_waitcnt lgkmcnt(12)
	v_mfma_f32_32x32x16_bf16 v[18:33], v[62:65], v[158:161], v[18:33]
	s_waitcnt lgkmcnt(10)
	v_mfma_f32_32x32x16_bf16 v[34:49], v[50:53], v[70:73], v[34:49]
	s_waitcnt lgkmcnt(8)
	v_mfma_f32_32x32x16_bf16 v[18:33], v[50:53], v[162:165], v[18:33]
	s_waitcnt lgkmcnt(6)
	v_mfma_f32_32x32x16_bf16 v[34:49], v[54:57], v[74:77], v[34:49]
	s_waitcnt lgkmcnt(4)
	v_mfma_f32_32x32x16_bf16 v[18:33], v[54:57], v[166:169], v[18:33]
	v_add_u32_e32 v54, s5, v146
	v_add_u32_e32 v55, v54, v147
	ds_read_b128 v[50:53], v55 offset:49152
	ds_read_b128 v[158:161], v55 offset:57344
	v_add_u32_e32 v55, v54, v148
	ds_read_b128 v[162:165], v55 offset:49152
	ds_read_b128 v[166:169], v55 offset:57344
	v_add_u32_e32 v55, v54, v149
	s_waitcnt lgkmcnt(6)
	v_mfma_f32_32x32x16_bf16 v[34:49], v[58:61], v[78:81], v[34:49]
	s_waitcnt lgkmcnt(4)
	v_mfma_f32_32x32x16_bf16 v[18:33], v[58:61], v[170:173], v[18:33]
	ds_read_b128 v[170:173], v55 offset:49152
	ds_read_b128 v[178:181], v55 offset:57344
	v_add_u32_e32 v55, v54, v150
	ds_read_b128 v[182:185], v55 offset:49152
	ds_read_b128 v[186:189], v55 offset:57344
	v_add_u32_e32 v55, v54, v151
	v_add_u32_e32 v54, v54, v152
	ds_read_b128 v[190:193], v55 offset:49152
	ds_read_b128 v[194:197], v55 offset:57344
	ds_read_b128 v[198:201], v54 offset:49152
	ds_read_b128 v[202:205], v54 offset:57344
	s_waitcnt lgkmcnt(11)
	v_mfma_f32_32x32x16_bf16 v[66:81], v[50:53], v[82:85], v[2:17]
	s_waitcnt lgkmcnt(10)
	v_mfma_f32_32x32x16_bf16 v[50:65], v[158:161], v[82:85], v[2:17]
	s_waitcnt lgkmcnt(9)
	v_mfma_f32_32x32x16_bf16 v[66:81], v[162:165], v[86:89], v[66:81]
	s_waitcnt lgkmcnt(8)
	v_mfma_f32_32x32x16_bf16 v[50:65], v[166:169], v[86:89], v[50:65]
	s_waitcnt lgkmcnt(7)
	v_mfma_f32_32x32x16_bf16 v[66:81], v[170:173], v[90:93], v[66:81]
	s_waitcnt lgkmcnt(6)
	v_mfma_f32_32x32x16_bf16 v[50:65], v[178:181], v[90:93], v[50:65]
	s_waitcnt lgkmcnt(5)
	v_mfma_f32_32x32x16_bf16 v[66:81], v[182:185], v[94:97], v[66:81]
	s_waitcnt lgkmcnt(4)
	v_mfma_f32_32x32x16_bf16 v[50:65], v[186:189], v[94:97], v[50:65]
	s_waitcnt lgkmcnt(3)
	v_mfma_f32_32x32x16_bf16 v[66:81], v[190:193], v[98:101], v[66:81]
	s_waitcnt lgkmcnt(2)
	v_mfma_f32_32x32x16_bf16 v[50:65], v[194:197], v[98:101], v[50:65]
	s_waitcnt lgkmcnt(1)
	v_mfma_f32_32x32x16_bf16 v[66:81], v[198:201], v[102:105], v[66:81]
	s_waitcnt lgkmcnt(0)
	v_mfma_f32_32x32x16_bf16 v[50:65], v[202:205], v[102:105], v[50:65]
	s_setprio 0
	s_nop 8
	v_max_f32_e32 v158, v67, v67
	v_max_f32_e32 v159, v66, v66
	v_max_f32_e32 v158, v159, v158
	v_max3_f32 v159, v68, v69, v51
	v_max3_f32 v158, v158, v50, v52
	v_max3_f32 v158, v158, v53, v70
	v_max3_f32 v159, v159, v72, v73
	v_max3_f32 v158, v158, v71, v54
	v_max3_f32 v159, v159, v56, v57
	v_max3_f32 v158, v158, v55, v74
	v_max3_f32 v159, v159, v76, v77
	v_max3_f32 v158, v158, v75, v58
	v_max3_f32 v159, v159, v60, v61
	v_max3_f32 v158, v158, v59, v78
	v_max3_f32 v159, v159, v80, v81
	v_max3_f32 v158, v158, v79, v62
	v_max3_f32 v159, v159, v64, v65
	v_max3_f32 v158, v158, v63, v159
	v_mov_b32_e32 v159, v158
	s_nop 1
	v_permlane32_swap_b32_e32 v158, v159
	v_max_f32_e32 v159, v159, v159
	v_max_f32_e32 v158, v158, v158
	v_max_f32_e32 v159, v158, v159
	v_cmp_ge_f32_e32 vcc, s93, v159
	s_cmp_eq_u64 vcc, exec
	v_mov_b32_e32 v158, 1.0
	s_barrier
	s_cbranch_scc0 .LBB0_540

; __device__ __forceinline__ void softmaxT(f32x16& p0, f32x16& p1, float& mref, f32x16& negm, float& l_reg, float& alpha, bf16x8& pa0, bf16x8& pa1, bf16x8& pa2, bf16x8& pa3) {
;     ...
;   { float s0 = p0[0] + p1[0], s1 = p0[1] + p1[1], s2 = p0[2] + p1[2], s3 = p0[3] + p1[3];
; #pragma unroll
;     for (int r = 4; r < 16; r += 4) { s0 += p0[r] + p1[r]; s1 += p0[r + 1] + p1[r + 1]; s2 += p0[r + 2] + p1[r + 2]; s3 += p0[r + 3] + p1[r + 3]; }
;     l_reg += (s0 + s1) + (s2 + s3); }
; __device__ __forceinline__ void qkt(f32x16& p0, f32x16& p1, const LAS unsigned char* Ks, const bf16x8* qr, const f32x16& negm, int r32, int hi) {
;   bf16x8 kf[12];
; #pragma unroll
;   for (int d0 = 0; d0 < 6; ++d0) { const int cb = (d0 * 16 + hi * 8) * 2;
;     kf[2 * d0] = *(const LAS bf16x8*)(Ks + KSWZ(r32, cb)); kf[2 * d0 + 1] = *(const LAS bf16x8*)(Ks + KSWZ(32 + r32, cb)); }
;   SBAR();
;   p0 = __builtin_amdgcn_mfma_f32_32x32x16_bf16(kf[0], qr[0], negm, 0, 0, 0); p1 = __builtin_amdgcn_mfma_f32_32x32x16_bf16(kf[1], qr[0], negm, 0, 0, 0);
; #pragma unroll
;   for (int d0 = 1; d0 < 6; ++d0) { p0 = __builtin_amdgcn_mfma_f32_32x32x16_bf16(kf[2 * d0], qr[d0], p0, 0, 0, 0); p1 = __builtin_amdgcn_mfma_f32_32x32x16_bf16(kf[2 * d0 + 1], qr[d0], p1, 0, 0, 0); }
; }
; __device__ __forceinline__ int v_st(int k, int c) { const int kk = (k & ~0xC) | ((k & 4) << 1) | ((k & 8) >> 1); return ((kk >> 3) * 4 + (c >> 5)) * 512 + ((kk & 7) * 32 + (c & 31)) * 2; }
; __device__ __forceinline__ int v_rd_base(int lane) { return ((lane & 3) << 3) | (((lane >> 2) & 3) << 6) | (((lane >> 4) & 1) << 5) | (((lane >> 5) & 1) << 8); }
; template <int OFF> __device__ __forceinline__ s16x4 tr_read(int vb) {
;   s16x4 r; asm volatile("ds_read_b64_tr_b16 %0, %1 offset:%2" : "=&v"(r) : "v"(vb), "i"(OFF) : "memory"); return r;
; }
; __device__ __forceinline__ void pv_d0(f32x16* o, int vb, bf16x8 pa0, bf16x8 pa1, bf16x8 pa2, bf16x8 pa3) {
;   const s16x4 a0 = tr_read<v_rd_off(0, 0, 0)>(vb), b0 = tr_read<v_rd_off(0, 0, 1)>(vb), a1 = tr_read<v_rd_off(0, 1, 0)>(vb), b1 = tr_read<v_rd_off(0, 1, 1)>(vb);
;   const s16x4 a2 = tr_read<v_rd_off(0, 2, 0)>(vb), b2 = tr_read<v_rd_off(0, 2, 1)>(vb), a3 = tr_read<v_rd_off(0, 3, 0)>(vb), b3 = tr_read<v_rd_off(0, 3, 1)>(vb);
;   const s16x4 c0 = tr_read<v_rd_off(1, 0, 0)>(vb), d0 = tr_read<v_rd_off(1, 0, 1)>(vb), c1 = tr_read<v_rd_off(1, 1, 0)>(vb), d1 = tr_read<v_rd_off(1, 1, 1)>(vb);
.LBB0_531:
	v_add_f32_e32 v66, v159, v66
	v_add_f32_e32 v70, v179, v70
	v_add_f32_e32 v67, v160, v67
	v_add_f32_e32 v66, v70, v66
	v_add_f32_e32 v70, v180, v71
	v_add_f32_e32 v68, v161, v68
	v_add_f32_e32 v67, v70, v67
	v_add_f32_e32 v70, v181, v72
	v_add_f32_e32 v69, v178, v69
	v_add_f32_e32 v68, v70, v68
	v_add_f32_e32 v70, v182, v73
	v_add_f32_e32 v69, v70, v69
	v_add_f32_e32 v70, v183, v74
	v_add_f32_e32 v66, v70, v66
	v_add_f32_e32 v70, v184, v75
	v_add_f32_e32 v67, v70, v67
	v_add_f32_e32 v70, v185, v76
	v_add_f32_e32 v68, v70, v68
	v_add_f32_e32 v70, v186, v77
	v_add_f32_e32 v69, v70, v69
	v_add_f32_e32 v70, v187, v78
	v_add_f32_e32 v66, v70, v66
	v_add_f32_e32 v70, v188, v79
	v_add_f32_e32 v67, v70, v67
	v_add_f32_e32 v70, v189, v80
	v_add_f32_e32 v68, v70, v68
	v_add_f32_e32 v70, v190, v81
	v_add_f32_e32 v69, v70, v69
	v_add_f32_e32 v66, v67, v66
	v_add_f32_e32 v67, v69, v68
	v_add_f32_e32 v66, v67, v66
	v_add_f32_e32 v157, v157, v66
	s_waitcnt lgkmcnt(0)
	s_barrier
	s_setprio 2
	v_add_u32_e32 v174, s5, v156
	ds_read_b64_tr_b16 v[66:67], v174 offset:0
	ds_read_b64_tr_b16 v[68:69], v174 offset:0x800
	ds_read_b64_tr_b16 v[158:159], v174 offset:0x200
	ds_read_b64_tr_b16 v[160:161], v174 offset:0xa00
	ds_read_b64_tr_b16 v[70:71], v174 offset:0x1000
	ds_read_b64_tr_b16 v[72:73], v174 offset:0x1800
	ds_read_b64_tr_b16 v[162:163], v174 offset:0x1200
	ds_read_b64_tr_b16 v[164:165], v174 offset:0x1a00
	ds_read_b64_tr_b16 v[74:75], v174 offset:0x2000
	ds_read_b64_tr_b16 v[76:77], v174 offset:0x2800
	ds_read_b64_tr_b16 v[166:167], v174 offset:0x2200
	ds_read_b64_tr_b16 v[168:169], v174 offset:0x2a00
	ds_read_b64_tr_b16 v[78:79], v174 offset:0x3000
	ds_read_b64_tr_b16 v[80:81], v174 offset:0x3800
	ds_read_b64_tr_b16 v[170:171], v174 offset:0x3200
	ds_read_b64_tr_b16 v[172:173], v174 offset:0x3a00
	s_waitcnt lgkmcnt(14)
	v_mfma_f32_32x32x16_bf16 v[34:49], v[54:57], v[66:69], v[34:49]
	s_waitcnt lgkmcnt(12)
	v_mfma_f32_32x32x16_bf16 v[18:33], v[54:57], v[158:161], v[18:33]
	v_add_u32_e32 v54, s10, v146
	v_add_u32_e32 v55, v54, v147
	s_waitcnt lgkmcnt(10)
	v_mfma_f32_32x32x16_bf16 v[34:49], v[50:53], v[70:73], v[34:49]
	s_waitcnt lgkmcnt(8)
	v_mfma_f32_32x32x16_bf16 v[18:33], v[50:53], v[162:165], v[18:33]
	ds_read_b128 v[50:53], v55 offset:49152
	ds_read_b128 v[158:161], v55 offset:57344
	v_add_u32_e32 v55, v54, v148
	s_waitcnt lgkmcnt(8)
	v_mfma_f32_32x32x16_bf16 v[34:49], v[58:61], v[74:77], v[34:49]
	s_waitcnt lgkmcnt(6)
	v_mfma_f32_32x32x16_bf16 v[18:33], v[58:61], v[166:169], v[18:33]
	ds_read_b128 v[162:165], v55 offset:49152
	ds_read_b128 v[166:169], v55 offset:57344
	v_add_u32_e32 v55, v54, v149
	s_waitcnt lgkmcnt(6)
	v_mfma_f32_32x32x16_bf16 v[34:49], v[62:65], v[78:81], v[34:49]
	s_waitcnt lgkmcnt(4)
	v_mfma_f32_32x32x16_bf16 v[18:33], v[62:65], v[170:173], v[18:33]
	ds_read_b128 v[170:173], v55 offset:49152
	ds_read_b128 v[178:181], v55 offset:57344
	v_add_u32_e32 v55, v54, v150
	ds_read_b128 v[182:185], v55 offset:49152
	ds_read_b128 v[186:189], v55 offset:57344
	v_add_u32_e32 v55, v54, v151
	v_add_u32_e32 v54, v54, v152
	ds_read_b128 v[190:193], v55 offset:49152
	ds_read_b128 v[194:197], v55 offset:57344
	ds_read_b128 v[198:201], v54 offset:49152
	ds_read_b128 v[202:205], v54 offset:57344
	s_waitcnt lgkmcnt(11)
	v_mfma_f32_32x32x16_bf16 v[66:81], v[50:53], v[82:85], v[2:17]
	s_waitcnt lgkmcnt(10)
	v_mfma_f32_32x32x16_bf16 v[50:65], v[158:161], v[82:85], v[2:17]
	s_waitcnt lgkmcnt(9)
	v_mfma_f32_32x32x16_bf16 v[66:81], v[162:165], v[86:89], v[66:81]
	s_waitcnt lgkmcnt(8)
	v_mfma_f32_32x32x16_bf16 v[50:65], v[166:169], v[86:89], v[50:65]
	s_waitcnt lgkmcnt(7)
	v_mfma_f32_32x32x16_bf16 v[66:81], v[170:173], v[90:93], v[66:81]
	s_waitcnt lgkmcnt(6)
	v_mfma_f32_32x32x16_bf16 v[50:65], v[178:181], v[90:93], v[50:65]
	s_waitcnt lgkmcnt(5)
	v_mfma_f32_32x32x16_bf16 v[66:81], v[182:185], v[94:97], v[66:81]
	s_waitcnt lgkmcnt(4)
	v_mfma_f32_32x32x16_bf16 v[50:65], v[186:189], v[94:97], v[50:65]
	s_waitcnt lgkmcnt(3)
	v_mfma_f32_32x32x16_bf16 v[66:81], v[190:193], v[98:101], v[66:81]
	s_waitcnt lgkmcnt(2)
	v_mfma_f32_32x32x16_bf16 v[50:65], v[194:197], v[98:101], v[50:65]
	s_waitcnt lgkmcnt(1)
	v_mfma_f32_32x32x16_bf16 v[66:81], v[198:201], v[102:105], v[66:81]
	s_waitcnt lgkmcnt(0)
	v_mfma_f32_32x32x16_bf16 v[50:65], v[202:205], v[102:105], v[50:65]
	s_setprio 0
	s_nop 8
	v_max_f32_e32 v158, v67, v67
	v_max_f32_e32 v159, v66, v66
	v_max_f32_e32 v158, v159, v158
	v_max3_f32 v159, v68, v69, v51
	v_max3_f32 v158, v158, v50, v52
	v_max3_f32 v158, v158, v53, v70
	v_max3_f32 v159, v159, v72, v73
	v_max3_f32 v158, v158, v71, v54
	v_max3_f32 v159, v159, v56, v57
	v_max3_f32 v158, v158, v55, v74
	v_max3_f32 v159, v159, v76, v77
	v_max3_f32 v158, v158, v75, v58
	v_max3_f32 v159, v159, v60, v61
	v_max3_f32 v158, v158, v59, v78
	v_max3_f32 v159, v159, v80, v81
	v_max3_f32 v158, v158, v79, v62
	v_max3_f32 v159, v159, v64, v65
	v_max3_f32 v158, v158, v63, v159
	v_mov_b32_e32 v159, v158
	s_nop 1
	v_permlane32_swap_b32_e32 v158, v159
	v_max_f32_e32 v159, v159, v159
	v_max_f32_e32 v158, v158, v158
	v_max_f32_e32 v159, v158, v159
	v_cmp_ge_f32_e32 vcc, s93, v159
	s_cmp_eq_u64 vcc, exec
	v_mov_b32_e32 v158, 1.0
	s_barrier
	s_cbranch_scc0 .LBB0_541

; #define PHASE_M(j) do { SBAR(); __builtin_amdgcn_s_setprio(2); if ((j) > 0) pv_d0(o, vb0 + bV, pa0, pa1, pa2, pa3); qkt(p0, p1, Kb + bK, qr, negm, r32, hi); __builtin_amdgcn_s_setprio(0); SBAR(); __syncthreads(); } while (0)
; #define PHASE_V(j, slot) do { softmaxT(p0, p1, mref, negm, l_reg, alpha, pa0, pa1, pa2, pa3); RESC(alpha); \
;     { const int s_ = (j) + 1 + trail; if (s_ < NT) { asm volatile("s_waitcnt vmcnt(3)" ::: "memory"); SWRITE_AT(trail ? bNN : bN, slot); const int s2_ = s_ + 2; SLOAD(slot, s2_ < NT ? s2_ : NT - 1); } } \
;     __syncthreads(); bV = bK; bK = bN; bN = bNN; bNN = bV; } while (0)
; __device__ __forceinline__ void softmaxT(f32x16& p0, f32x16& p1, float& mref, f32x16& negm, float& l_reg, float& alpha, bf16x8& pa0, bf16x8& pa1, bf16x8& pa2, bf16x8& pa3) {
;     ...
;   { float s0 = p0[0] + p1[0], s1 = p0[1] + p1[1], s2 = p0[2] + p1[2], s3 = p0[3] + p1[3];
; #pragma unroll
;     for (int r = 4; r < 16; r += 4) { s0 += p0[r] + p1[r]; s1 += p0[r + 1] + p1[r + 1]; s2 += p0[r + 2] + p1[r + 2]; s3 += p0[r + 3] + p1[r + 3]; }
;     l_reg += (s0 + s1) + (s2 + s3); }
; __device__ __forceinline__ void attn_unit(const bf16_t* __restrict__ Qb, bool rope_q, int tq0, const bf16_t* __restrict__ KVh, const bf16_t* __restrict__ KR,
;                                           int ctx_row0, int lat_row0, int NT, bf16_t* __restrict__ Ob, LAS unsigned char* lds, int wave_s) {
;     ...
;   for (int j = 0; j < NT; j += 2) {
;     PHASE_M(j); PHASE_V(j, 1);
;     PHASE_M(j + 1); PHASE_V(j + 1, 0);
;   }
.LBB0_538:
	v_add_f32_e32 v66, v159, v66
	v_add_f32_e32 v70, v179, v70
	v_add_f32_e32 v67, v160, v67
	v_add_f32_e32 v66, v70, v66
	v_add_f32_e32 v70, v180, v71
	v_add_f32_e32 v68, v161, v68
	v_add_f32_e32 v67, v70, v67
	v_add_f32_e32 v70, v181, v72
	v_add_f32_e32 v69, v178, v69
	v_add_f32_e32 v68, v70, v68
	v_add_f32_e32 v70, v182, v73
	v_add_f32_e32 v69, v70, v69
	v_add_f32_e32 v70, v183, v74
	v_add_f32_e32 v66, v70, v66
	v_add_f32_e32 v70, v184, v75
	v_add_f32_e32 v67, v70, v67
	v_add_f32_e32 v70, v185, v76
	v_add_f32_e32 v68, v70, v68
	v_add_f32_e32 v70, v186, v77
	v_add_f32_e32 v69, v70, v69
	v_add_f32_e32 v70, v187, v78
	v_add_f32_e32 v66, v70, v66
	v_add_f32_e32 v70, v188, v79
	v_add_f32_e32 v67, v70, v67
	v_add_f32_e32 v70, v189, v80
	v_add_f32_e32 v68, v70, v68
	v_add_f32_e32 v70, v190, v81
	v_add_f32_e32 v69, v70, v69
	v_add_f32_e32 v66, v67, v66
	v_add_f32_e32 v67, v69, v68
	v_add_f32_e32 v66, v67, v66
	s_add_i32 s11, s11, 2
	v_add_f32_e32 v157, v157, v66
	s_and_b64 vcc, exec, s[0:1]
	s_waitcnt lgkmcnt(0)
	s_barrier
	s_cbranch_vccnz .LBB0_542
	s_mov_b32 s0, s10
	s_mov_b32 s10, s5
	s_mov_b32 s5, s22
	s_branch .LBB0_524
